# attention local-tile loops: K (and NAT V) fragment LDS reads batched up front with counted lgkmcnt, NAT V halves read straight into MFMA operand order (no v_mov shuffles)
# speedup vs baseline: 1.0138x; 1.0092x over previous
; #define LAS __attribute__((address_space(3)))
; DI float shx(float v, int m, int lane) { return __builtin_bit_cast(float, __builtin_amdgcn_ds_bpermute((lane ^ m) << 2, __builtin_bit_cast(int, v))); }
; #define MFMA16(a, b, c) __builtin_amdgcn_mfma_f32_16x16x32_bf16((a), (b), (c), 0, 0, 0)
; template <bool SWA>
; DI void attn_phase(const Ctx& a, LAS unsigned char* lds) {
;     ...
;             if (nck == 2) {
;                 const int tkey0 = rlo + 64 * tl;
;                 f32x4 sc[4];
; #pragma unroll
;                 for (int jt = 0; jt < 4; ++jt) {
;                     const int row = 16 * jt + fr; const int sw = (row >> 1) & 7;
;                     const bf16x8 k0 = *(const LAS bf16x8*)(lds + AT_K + buf * 8192 + row * 128 + ((fq ^ sw) << 4));
;                     const bf16x8 k1 = *(const LAS bf16x8*)(lds + AT_K + buf * 8192 + row * 128 + (((4 + fq) ^ sw) << 4));
;                     f32x4 acc = (f32x4){0.f, 0.f, 0.f, 0.f}; acc = MFMA16(k0, qf[0], acc); acc = MFMA16(k1, qf[1], acc); sc[jt] = acc;
;                 }
;                 float sv[16]; bool ok[16];
; #pragma unroll
;                 for (int jt = 0; jt < 4; ++jt)
; #pragma unroll
;                     for (int rr = 0; rr < 4; ++rr) {
;                         bool valid = true;
;                         if (SWA && local) { const int dd = tkey0 + 16 * jt + 4 * fq + rr - (tq0 + fr); valid = (dd <= 128) && (dd >= -128); }
;                         sv[jt * 4 + rr] = valid ? sc[jt][rr] : -1e30f; ok[jt * 4 + rr] = valid;
;                     }
;                 float cmax = sv[0];
; #pragma unroll
;                 for (int e = 1; e < 16; ++e) cmax = fmaxf(cmax, sv[e]);
;                 cmax = fmaxf(cmax, shx(cmax, 16, lane)); cmax = fmaxf(cmax, shx(cmax, 32, lane));
;                 const float m_new = fmaxf(m_run, cmax);
.LBB0_113:
	s_lshl_b32 s79, s78, 13
	v_add_u32_e32 v24, s79, v65
	v_add_u32_e32 v38, v24, v66
	v_add_u32_e32 v24, v24, v67
	ds_read_b128 v[116:119], v38
	ds_read_b128 v[120:123], v24
	ds_read_b128 v[124:127], v38 offset:2048
	ds_read_b128 v[128:131], v24 offset:2048
	ds_read_b128 v[132:135], v38 offset:4096
	ds_read_b128 v[136:139], v24 offset:4096
	ds_read_b128 v[84:87], v38 offset:6144
	ds_read_b128 v[88:91], v24 offset:6144
	s_movk_i32 s20, 0x101
	s_waitcnt lgkmcnt(6)
	v_mfma_f32_16x16x32_bf16 v[28:31], v[116:119], v[12:15], 0
	v_mfma_f32_16x16x32_bf16 v[30:33], v[120:123], v[16:19], v[28:31]
	s_waitcnt lgkmcnt(4)
	v_mfma_f32_16x16x32_bf16 v[34:37], v[124:127], v[12:15], 0
	v_mfma_f32_16x16x32_bf16 v[34:37], v[128:131], v[16:19], v[34:37]
	s_waitcnt lgkmcnt(2)
	v_mfma_f32_16x16x32_bf16 v[80:83], v[132:135], v[12:15], 0
	v_mfma_f32_16x16x32_bf16 v[80:83], v[136:139], v[16:19], v[80:83]
	v_add_u32_e32 v24, s75, v26
	v_add_u32_e32 v28, 0x80, v24
	v_cmp_gt_u32_e64 s[66:67], s20, v28
	v_add_u32_e32 v28, 0x81, v24
	v_cmp_gt_u32_e64 s[70:71], s20, v28
	v_add_u32_e32 v28, 0x82, v24
	v_cmp_gt_u32_e64 s[68:69], s20, v28
	v_add_u32_e32 v28, 0x83, v24
	v_cmp_gt_u32_e64 s[64:65], s20, v28
	v_add_u32_e32 v28, 0x90, v24
	v_cmp_gt_u32_e64 s[62:63], s20, v28
	v_add_u32_e32 v28, 0x91, v24
	v_cmp_gt_u32_e64 s[60:61], s20, v28
	v_add_u32_e32 v28, 0x92, v24
	v_cmp_gt_u32_e64 s[58:59], s20, v28
	v_add_u32_e32 v28, 0x93, v24
	v_cmp_gt_u32_e64 s[56:57], s20, v28
	v_add_u32_e32 v28, 0xa0, v24
	v_cmp_gt_u32_e64 s[54:55], s20, v28
	v_add_u32_e32 v28, 0xa1, v24
	v_cmp_gt_u32_e64 s[52:53], s20, v28
	v_add_u32_e32 v28, 0xa2, v24
	v_cmp_gt_u32_e64 s[50:51], s20, v28
	v_add_u32_e32 v28, 0xa3, v24
	v_cmp_gt_u32_e64 s[48:49], s20, v28
	v_add_u32_e32 v28, 0xb0, v24
	s_waitcnt lgkmcnt(0)
	v_mfma_f32_16x16x32_bf16 v[84:87], v[84:87], v[12:15], 0
	v_cmp_gt_u32_e64 s[46:47], s20, v28
	v_add_u32_e32 v28, 0xb1, v24
	v_cndmask_b32_e64 v29, v202, v30, s[66:67]
	v_cndmask_b32_e64 v30, v202, v31, s[70:71]
	v_cmp_gt_u32_e64 s[44:45], s20, v28
	v_add_u32_e32 v28, 0xb2, v24
	v_add_u32_e32 v24, 0xb3, v24
	v_cmp_gt_u32_e64 s[42:43], s20, v28
	v_cmp_gt_u32_e64 s[40:41], s20, v24
	v_max_f32_e32 v24, v30, v30
	v_max_f32_e32 v28, v29, v29
	v_cndmask_b32_e64 v31, v202, v32, s[68:69]
	v_cndmask_b32_e64 v32, v202, v33, s[64:65]
	v_max_f32_e32 v24, v28, v24
	v_mfma_f32_16x16x32_bf16 v[84:87], v[88:91], v[16:19], v[84:87]
	v_cndmask_b32_e64 v33, v202, v34, s[62:63]
	v_cndmask_b32_e64 v34, v202, v35, s[60:61]
	v_max3_f32 v24, v24, v31, v32
	v_cndmask_b32_e64 v35, v202, v36, s[58:59]
	v_cndmask_b32_e64 v36, v202, v37, s[56:57]
	v_max3_f32 v24, v24, v33, v34
	v_cndmask_b32_e64 v37, v202, v80, s[54:55]
	v_cndmask_b32_e64 v38, v202, v81, s[52:53]
	v_max3_f32 v24, v24, v35, v36
	v_cndmask_b32_e64 v39, v202, v82, s[50:51]
	v_cndmask_b32_e64 v49, v202, v83, s[48:49]
	v_max3_f32 v24, v24, v37, v38
	v_cndmask_b32_e64 v51, v202, v84, s[46:47]
	v_cndmask_b32_e64 v55, v202, v85, s[44:45]
	v_max3_f32 v24, v24, v39, v49
	v_cndmask_b32_e64 v60, v202, v86, s[42:43]
	v_cndmask_b32_e64 v76, v202, v87, s[40:41]
	v_max3_f32 v24, v24, v51, v55
	v_max3_f32 v24, v24, v60, v76
	ds_bpermute_b32 v28, v68, v24
	s_waitcnt lgkmcnt(0)
	v_max_f32_e32 v28, v28, v28
	v_max_f32_e32 v24, v24, v28
	ds_bpermute_b32 v28, v69, v24
	s_waitcnt lgkmcnt(0)
	v_max3_f32 v28, v79, v24, v28
	v_sub_f32_e32 v24, v79, v28
	v_mul_f32_e32 v24, 0x3fb8aa3b, v24
	v_exp_f32_e32 v24, v24
	s_nop 0
	v_cmp_neq_f32_e32 vcc, 1.0, v24
	s_cbranch_vccz .LBB0_115
	v_pk_mul_f32 v[6:7], v[6:7], v[24:25] op_sel_hi:[1,0]
	v_pk_mul_f32 v[4:5], v[4:5], v[24:25] op_sel_hi:[1,0]
	v_pk_mul_f32 v[10:11], v[10:11], v[24:25] op_sel_hi:[1,0]
	v_pk_mul_f32 v[8:9], v[8:9], v[24:25] op_sel_hi:[1,0]
	v_pk_mul_f32 v[22:23], v[22:23], v[24:25] op_sel_hi:[1,0]
	v_pk_mul_f32 v[20:21], v[20:21], v[24:25] op_sel_hi:[1,0]
	v_pk_mul_f32 v[2:3], v[2:3], v[24:25] op_sel_hi:[1,0]
	v_pk_mul_f32 v[0:1], v[0:1], v[24:25] op_sel_hi:[1,0]

; #define LAS __attribute__((address_space(3)))
; template <bool SWA>
; DI void attn_phase(const Ctx& a, LAS unsigned char* lds) {
;     ...
;             for (int ck = 0; ck < nck; ++ck) {
;                 const int ko = k0off + 32 * ck;
;                 int tkey0 = 0;
;                 if (SWA && local) { tkey0 = rlo + 64 * tl + ko; if (tkey0 + 31 < tq0 - 128 || tkey0 > tq0 + 15 + 128) continue; }
;                 f32x4 sc[2];
; #pragma unroll
;                 for (int jt = 0; jt < 2; ++jt) {
;                     const int row = ko + 16 * jt + fr; const int sw = (row >> 1) & 7;
;                     const bf16x8 k0 = *(const LAS bf16x8*)(lds + AT_K + buf * 8192 + row * 128 + ((fq ^ sw) << 4));
;                     const bf16x8 k1 = *(const LAS bf16x8*)(lds + AT_K + buf * 8192 + row * 128 + (((4 + fq) ^ sw) << 4));
;                     f32x4 acc = (f32x4){0.f, 0.f, 0.f, 0.f}; acc = MFMA16(k0, qf[0], acc); acc = MFMA16(k1, qf[1], acc); sc[jt] = acc;
;                 }
;                 float sv[8]; bool ok[8];
; #pragma unroll
;                 for (int jt = 0; jt < 2; ++jt)
; #pragma unroll
;                     for (int rr = 0; rr < 4; ++rr) {
;                         const int jj = 16 * jt + 4 * fq + rr; float x = sc[jt][rr]; bool valid = true;
;                         if (local) {
;                             if (!SWA) { x += bias[jt * 4 + rr]; }
;                             else { const int dd = tkey0 + jj - (tq0 + fr); valid = (dd <= 128) && (dd >= -128); }
;                         }
;                         sv[jt * 4 + rr] = valid ? x : -1e30f; ok[jt * 4 + rr] = valid;
;                     }
;                 float cmax = sv[0];
; #pragma unroll
;                 for (int e = 1; e < 8; ++e) cmax = fmaxf(cmax, sv[e]);
;                 cmax = fmaxf(cmax, shx(cmax, 16, lane)); cmax = fmaxf(cmax, shx(cmax, 32, lane));
;                 const float m_new = fmaxf(m_run, cmax);
;                 const float alpha = __builtin_amdgcn_exp2f((m_run - m_new) * LOG2E);
;                 float p[8], psum = 0.f;
; #pragma unroll
;                 for (int e = 0; e < 8; ++e) { p[e] = ok[e] ? __builtin_amdgcn_exp2f((sv[e] - m_new) * LOG2E) : 0.f; psum += p[e]; }
;                 l_run = l_run * alpha + psum; m_run = m_new;
;                 u32x4 pw; pw.x = pk2(p[0], p[1]); pw.y = pk2(p[2], p[3]); pw.z = pk2(p[4], p[5]); pw.w = pk2(p[6], p[7]);
.LBB0_180:
	s_add_i32 s20, s16, s48
	v_cmp_ge_i32_e32 vcc, s20, v51
	v_cmp_le_i32_e64 s[42:43], s20, v25
	s_and_b64 s[20:21], vcc, s[42:43]
	s_and_saveexec_b64 s[42:43], s[20:21]
	s_cbranch_execz .LBB0_185
	s_lshl_b32 s49, s45, 13
	s_waitcnt lgkmcnt(0)
	v_add_u32_e32 v116, s49, v87
	v_add_u32_e32 v117, v116, v81
	v_add_u32_e32 v118, v116, v86
	ds_read_b128 v[120:123], v117
	ds_read_b128 v[124:127], v118
	ds_read_b128 v[128:131], v117 offset:2048
	ds_read_b128 v[132:135], v118 offset:2048
	v_add_u32_e32 v116, s49, v74
	v_add3_u32 v117, v116, v84, v72
	v_add3_u32 v118, v116, v85, v72
	ds_read_b64 v[136:137], v117 offset:24576
	ds_read_b64 v[138:139], v118 offset:24576
	ds_read_b64 v[140:141], v117 offset:26624
	ds_read_b64 v[142:143], v118 offset:26624
	ds_read_b64 v[160:161], v117 offset:28672
	ds_read_b64 v[162:163], v118 offset:28672
	ds_read_b64 v[164:165], v117 offset:30720
	ds_read_b64 v[166:167], v118 offset:30720
	v_add_f32_e32 v106, v39, v94
	v_add_f32_e32 v102, v31, v90
	v_add_f32_e32 v103, v33, v91
	v_add_f32_e32 v104, v35, v92
	v_add_f32_e32 v105, v37, v93
	v_add_f32_e32 v107, v83, v95
	v_add_f32_e32 v24, v27, v24
	v_add_f32_e32 v89, v29, v89
	s_waitcnt lgkmcnt(10)
	v_mfma_f32_16x16x32_bf16 v[90:93], v[120:123], v[0:3], 0
	v_mfma_f32_16x16x32_bf16 v[90:93], v[124:127], v[4:7], v[90:93]
	s_waitcnt lgkmcnt(8)
	v_mfma_f32_16x16x32_bf16 v[94:97], v[128:131], v[0:3], 0
	v_mfma_f32_16x16x32_bf16 v[98:101], v[132:135], v[4:7], v[94:97]
	s_nop 6
	v_add_f32_e32 v97, v24, v90
	v_add_f32_e32 v96, v89, v91
	v_add_f32_e32 v95, v102, v92
	v_add_f32_e32 v94, v103, v93
	v_max_f32_e32 v24, v97, v96
	v_add_f32_e32 v93, v104, v98
	v_add_f32_e32 v92, v105, v99
	v_max3_f32 v24, v24, v95, v94
	v_add_f32_e32 v91, v106, v100
	v_add_f32_e32 v90, v107, v101
	v_max3_f32 v24, v24, v93, v92
	v_max3_f32 v24, v24, v91, v90
	ds_bpermute_b32 v89, v69, v24
	s_waitcnt lgkmcnt(0)
	v_max_f32_e32 v89, v89, v89
	v_max_f32_e32 v24, v24, v89
	ds_bpermute_b32 v89, v70, v24
	s_waitcnt lgkmcnt(0)
	v_max3_f32 v89, v49, v24, v89
	v_sub_f32_e32 v24, v49, v89
	v_mul_f32_e32 v24, 0x3fb8aa3b, v24
	v_exp_f32_e32 v24, v24
	s_nop 0
	v_cmp_neq_f32_e32 vcc, 1.0, v24
	s_cbranch_vccz .LBB0_183
	v_pk_mul_f32 v[14:15], v[14:15], v[24:25] op_sel_hi:[1,0]
	v_pk_mul_f32 v[12:13], v[12:13], v[24:25] op_sel_hi:[1,0]
	v_pk_mul_f32 v[18:19], v[18:19], v[24:25] op_sel_hi:[1,0]
	v_pk_mul_f32 v[16:17], v[16:17], v[24:25] op_sel_hi:[1,0]
	v_pk_mul_f32 v[22:23], v[22:23], v[24:25] op_sel_hi:[1,0]
	v_pk_mul_f32 v[20:21], v[20:21], v[24:25] op_sel_hi:[1,0]
	v_pk_mul_f32 v[10:11], v[10:11], v[24:25] op_sel_hi:[1,0]
	v_pk_mul_f32 v[8:9], v[8:9], v[24:25] op_sel_hi:[1,0]
.LBB0_183:
	v_sub_f32_e32 v97, v97, v89
	v_mul_f32_e32 v97, 0x3fb8aa3b, v97
	v_sub_f32_e32 v96, v96, v89
	v_exp_f32_e32 v97, v97
	v_mul_f32_e32 v96, 0x3fb8aa3b, v96
	v_sub_f32_e32 v95, v95, v89
	v_exp_f32_e32 v96, v96
	v_mul_f32_e32 v95, 0x3fb8aa3b, v95
	v_sub_f32_e32 v94, v94, v89
	v_exp_f32_e32 v95, v95
	v_mul_f32_e32 v94, 0x3fb8aa3b, v94
	v_sub_f32_e32 v93, v93, v89
	v_exp_f32_e32 v94, v94
	v_mul_f32_e32 v93, 0x3fb8aa3b, v93
	v_sub_f32_e32 v92, v92, v89
	v_add_f32_e32 v98, 0, v97
	v_exp_f32_e32 v93, v93
	v_mul_f32_e32 v92, 0x3fb8aa3b, v92
	v_sub_f32_e32 v91, v91, v89
	v_add_f32_e32 v98, v96, v98
	v_exp_f32_e32 v92, v92
	v_mul_f32_e32 v91, 0x3fb8aa3b, v91
	v_add_f32_e32 v98, v95, v98
	v_exp_f32_e32 v99, v91
	v_add_f32_e32 v98, v94, v98
	v_add_f32_e32 v98, v93, v98
	v_sub_f32_e32 v90, v90, v89
	v_add_f32_e32 v98, v92, v98
	v_mul_f32_e32 v90, 0x3fb8aa3b, v90
	v_add_f32_e32 v91, v99, v98
	v_exp_f32_e32 v98, v90
	v_cvt_pk_bf16_f32 v90, v97, v96
	v_cvt_pk_bf16_f32 v92, v93, v92
	v_add_f32_e32 v106, v98, v91
	v_fmac_f32_e32 v106, v88, v24
	v_cvt_pk_bf16_f32 v91, v95, v94
	v_cvt_pk_bf16_f32 v93, v99, v98
	v_mov_b32_e32 v88, v106
	v_readlane_b32 s49, v255, 19
	v_mov_b32_e32 v49, v89
	s_waitcnt lgkmcnt(0)
	v_mfma_f32_16x16x32_bf16 v[20:23], v[140:143], v[90:93], v[20:23]
	v_mfma_f32_16x16x32_bf16 v[8:11], v[136:139], v[90:93], v[8:11]
	v_mfma_f32_16x16x32_bf16 v[16:19], v[160:163], v[90:93], v[16:19]
	v_mfma_f32_16x16x32_bf16 v[12:15], v[164:167], v[90:93], v[12:15]
	s_or_b64 exec, exec, s[42:43]
	s_mov_b64 s[42:43], -1
	s_and_b64 vcc, exec, s[30:31]
	s_cbranch_vccnz .LBB0_186
